# s5_pass2 (layer 0): the 32 workgroups with a third ml_out unit give two s5_pass2 units to workgroups 64-127 (phase P+4 balance)
# baseline (speedup 1.0000x reference)
.LBB0_647:
	s_or_b64 exec, exec, s[4:5]
	s_brev_b32 s4, -2
	v_bfi_b32 v1, s4, v4, v1
	v_mul_f32_e32 v2, 0.5, v2
	v_add_f32_e32 v1, 1.0, v1
	v_mul_f32_e32 v1, v2, v1
	v_mul_f32_e32 v2, 0.5, v3
	v_bfi_b32 v3, s4, v6, v5
	v_add_f32_e32 v3, 1.0, v3
	v_mul_f32_e32 v2, v2, v3
	v_cvt_pk_bf16_f32 v1, v1, v2
	v_or_b32_e32 v2, 7, v30
	v_ashrrev_i32_e32 v3, 31, v2
	v_lshlrev_b64 v[2:3], 11, v[2:3]
	v_lshl_add_u64 v[2:3], v[28:29], 0, v[2:3]
	global_store_dwordx2 v[2:3], v[0:1], off
	s_load_dwordx2 s[4:5], s[0:1], 0x118
	s_waitcnt lgkmcnt(0)
	s_cmp_eq_u32 s33, 0x100
	s_cbranch_scc0 .Ls5b_std
	s_cmp_eq_u32 s72, 0
	s_cbranch_scc0 .Ls5b_std
	s_and_b32 s5, s8, 0xff
	s_cmpk_lt_u32 s5, 0xe0
	s_cbranch_scc1 .Ls5b_lo
	s_cmpk_gt_u32 s8, 0xff
	s_cbranch_scc1 .LBB0_780
	s_branch .Ls5b_std
.Ls5b_lo:
	s_lshr_b32 vcc_lo, s8, 8
	s_cmp_eq_u32 vcc_lo, 3
	s_cbranch_scc0 .Ls5b_std
	s_sub_u32 vcc_lo, s5, 64
	s_cmp_lt_u32 vcc_lo, 64
	s_cbranch_scc0 .Ls5b_std
	s_add_i32 s8, s5, 0x380
	s_cmp_lt_u32 s5, 96
	s_cbranch_scc0 .LBB0_648
	s_add_i32 s8, s5, 0x2a0
	s_branch .LBB0_648
.Ls5b_std:
	s_add_i32 s8, s4, s8
	s_cmpk_lt_i32 s8, 0x440
	s_cbranch_scc0 .LBB0_780
